# plain loop LDS-DMA issue without the m0 save/restore pair around each global_load_lds
# baseline (speedup 1.0000x reference)
.LBB0_309:
	s_mov_b32 s77, s74
	v_add3_u32 v215, s77, v209, v208
	v_add3_u32 v216, s77, v210, v208
	v_add3_u32 v233, s77, v211, v208
	v_add3_u32 v254, s77, v212, v208
	ds_read_b128 v[234:237], v215 offset:49152
	ds_read_b128 v[238:241], v215 offset:57344
	ds_read_b128 v[242:245], v216 offset:49152
	ds_read_b128 v[246:249], v216 offset:57344
	ds_read_b128 v[250:253], v233 offset:49152
	s_add_u32 s4, s70, 0xffffc000
	s_mov_b32 s74, s72
	s_addc_u32 s5, s71, -1
	s_add_i32 s72, s72, s42
	s_setprio 1
	s_waitcnt lgkmcnt(4)
	v_mfma_f32_32x32x16_bf16 v[112:127], v[234:237], v[188:191], 0
	ds_read_b128 v[234:237], v233 offset:57344
	v_add_f32_e32 v1, 0, v230
	v_add_f32_e32 v1, v232, v1
	v_add_f32_e32 v1, v228, v1
	v_add_f32_e32 v1, v231, v1
	v_add_f32_e32 v1, v226, v1
	s_waitcnt lgkmcnt(4)
	v_mfma_f32_32x32x16_bf16 v[96:111], v[238:241], v[188:191], 0
	ds_read_b128 v[238:241], v254 offset:49152
	v_add_f32_e32 v1, v229, v1
	v_add_f32_e32 v1, v225, v1
	v_add_f32_e32 v1, v227, v1
	v_add_f32_e32 v1, v222, v1
	v_add_f32_e32 v1, v224, v1
	s_waitcnt lgkmcnt(4)
	v_mfma_f32_32x32x16_bf16 v[112:127], v[242:245], v[184:187], v[112:127]
	ds_read_b128 v[242:245], v254 offset:57344
	s_mov_b32 m0, s72
	s_nop 0
	global_load_lds_dwordx4 v197, s[4:5]
	v_add_f32_e32 v1, v220, v1
	v_add_f32_e32 v1, v223, v1
	v_exp_f32_e32 v2, v128
	v_add_f32_e32 v1, v218, v1
	s_waitcnt lgkmcnt(4)
	v_mfma_f32_32x32x16_bf16 v[96:111], v[246:249], v[184:187], v[96:111]
	ds_read_b128 v[246:249], v215 offset:49280
	v_exp_f32_e32 v12, v129
	v_add_f32_e32 v1, v221, v1
	v_exp_f32_e32 v13, v130
	v_add_f32_e32 v1, v217, v1
	s_waitcnt lgkmcnt(4)
	v_mfma_f32_32x32x16_bf16 v[112:127], v[250:253], v[180:183], v[112:127]
	ds_read_b128 v[250:253], v215 offset:57472
	v_exp_f32_e32 v14, v131
	v_add_f32_e32 v1, v219, v1
	v_exp_f32_e32 v15, v132
	s_waitcnt lgkmcnt(4)
	v_mfma_f32_32x32x16_bf16 v[96:111], v[234:237], v[180:183], v[96:111]
	ds_read_b128 v[234:237], v216 offset:49280
	s_addk_i32 s72, 0x400
	s_mov_b32 m0, s72
	s_nop 0
	global_load_lds_dwordx4 v198, s[4:5]
	v_add_f32_e32 v1, v2, v1
	v_exp_f32_e32 v18, v133
	v_add_f32_e32 v1, v12, v1
	s_waitcnt lgkmcnt(4)
	v_mfma_f32_32x32x16_bf16 v[112:127], v[238:241], v[176:179], v[112:127]
	ds_read_b128 v[238:241], v216 offset:57472
	v_exp_f32_e32 v19, v134
	v_add_f32_e32 v1, v13, v1
	v_exp_f32_e32 v20, v135
	v_add_f32_e32 v1, v14, v1
	s_waitcnt lgkmcnt(4)
	v_mfma_f32_32x32x16_bf16 v[96:111], v[242:245], v[176:179], v[96:111]
	ds_read_b128 v[242:245], v233 offset:49280
	v_exp_f32_e32 v21, v136
	v_add_f32_e32 v1, v15, v1
	v_exp_f32_e32 v22, v137
	s_waitcnt lgkmcnt(4)
	v_mfma_f32_32x32x16_bf16 v[112:127], v[246:249], v[172:175], v[112:127]
	ds_read_b128 v[246:249], v233 offset:57472
	s_add_i32 s4, s69, s97
	s_mov_b32 m0, s4
	s_nop 0
	global_load_lds_dwordx4 v199, s[56:57]
	v_add_f32_e32 v1, v18, v1
	v_exp_f32_e32 v23, v138
	v_add_f32_e32 v1, v19, v1
	v_exp_f32_e32 v24, v139
	s_waitcnt lgkmcnt(4)
	v_mfma_f32_32x32x16_bf16 v[96:111], v[250:253], v[172:175], v[96:111]
	ds_read_b128 v[250:253], v254 offset:49280
	v_add_f32_e32 v1, v20, v1
	v_exp_f32_e32 v25, v140
	v_add_f32_e32 v1, v21, v1
	s_waitcnt lgkmcnt(4)
	v_mfma_f32_32x32x16_bf16 v[112:127], v[234:237], v[168:171], v[112:127]
	ds_read_b128 v[234:237], v254 offset:57472
	v_exp_f32_e32 v26, v141
	v_add_f32_e32 v1, v22, v1
	v_exp_f32_e32 v27, v142
	v_add_f32_e32 v1, v23, v1
	s_waitcnt lgkmcnt(4)
	v_mfma_f32_32x32x16_bf16 v[96:111], v[238:241], v[168:171], v[96:111]
	s_addk_i32 s4, 0x400
	s_mov_b32 m0, s4
	s_nop 0
	global_load_lds_dwordx4 v200, s[56:57]
	v_exp_f32_e32 v28, v143
	v_add_f32_e32 v1, v24, v1
	v_add_f32_e32 v1, v25, v1
	v_add_f32_e32 v1, v26, v1
	s_waitcnt lgkmcnt(3)
	v_mfma_f32_32x32x16_bf16 v[112:127], v[242:245], v[164:167], v[112:127]
	v_add_f32_e32 v1, v27, v1
	v_add_f32_e32 v1, v28, v1
	v_mov_b32_e32 v3, v1
	v_cvt_pk_bf16_f32 v4, v230, v232
	v_cvt_pk_bf16_f32 v5, v228, v231
	s_waitcnt lgkmcnt(2)
	v_mfma_f32_32x32x16_bf16 v[96:111], v[246:249], v[164:167], v[96:111]
	v_cvt_pk_bf16_f32 v6, v226, v229
	s_nop 1
	v_permlane32_swap_b32_e32 v1, v3
	v_cvt_pk_bf16_f32 v7, v225, v227
	v_cvt_pk_bf16_f32 v8, v222, v224
	v_cvt_pk_bf16_f32 v9, v220, v223
	s_waitcnt lgkmcnt(1)
	v_mfma_f32_32x32x16_bf16 v[112:127], v[250:253], v[160:163], v[112:127]
	v_cvt_pk_bf16_f32 v10, v218, v221
	v_cvt_pk_bf16_f32 v11, v217, v219
	v_cvt_pk_bf16_f32 v12, v2, v12
	v_cvt_pk_bf16_f32 v13, v13, v14
	v_cvt_pk_bf16_f32 v14, v15, v18
	s_waitcnt lgkmcnt(0)
	v_mfma_f32_32x32x16_bf16 v[96:111], v[234:237], v[160:163], v[96:111]
	v_cvt_pk_bf16_f32 v15, v19, v20
	v_cvt_pk_bf16_f32 v18, v21, v22
	v_cvt_pk_bf16_f32 v19, v23, v24
	v_cvt_pk_bf16_f32 v20, v25, v26
	v_cvt_pk_bf16_f32 v21, v27, v28
	s_setprio 0
	v_add_u32_e32 v2, s74, v206
	ds_read_b64_tr_b16 v[22:23], v2 offset:0
	ds_read_b64_tr_b16 v[24:25], v2 offset:0x800
	ds_read_b64_tr_b16 v[26:27], v2 offset:0x1000
	ds_read_b64_tr_b16 v[28:29], v2 offset:0x1800
	ds_read_b64_tr_b16 v[128:129], v2 offset:0x2000
	ds_read_b64_tr_b16 v[130:131], v2 offset:0x2800
	ds_read_b64_tr_b16 v[132:133], v2 offset:0x3000
	ds_read_b64_tr_b16 v[134:135], v2 offset:0x3800
	s_waitcnt lgkmcnt(6)
	s_nop 0
	v_mfma_f32_32x32x16_bf16 v[32:47], v[4:7], v[22:25], v[32:47]
	ds_read_b64_tr_b16 v[22:23], v2 offset:0x200
	ds_read_b64_tr_b16 v[24:25], v2 offset:0xa00
	s_waitcnt lgkmcnt(6)
	v_mfma_f32_32x32x16_bf16 v[32:47], v[8:11], v[26:29], v[32:47]
	ds_read_b64_tr_b16 v[26:27], v2 offset:0x1200
	ds_read_b64_tr_b16 v[28:29], v2 offset:0x1a00
	s_waitcnt lgkmcnt(6)
	v_mfma_f32_32x32x16_bf16 v[32:47], v[12:15], v[128:131], v[32:47]
	ds_read_b64_tr_b16 v[128:129], v2 offset:0x2200
	ds_read_b64_tr_b16 v[130:131], v2 offset:0x2a00
	s_waitcnt lgkmcnt(6)
	v_mfma_f32_32x32x16_bf16 v[32:47], v[18:21], v[132:135], v[32:47]
	ds_read_b64_tr_b16 v[132:133], v2 offset:0x3200
	ds_read_b64_tr_b16 v[134:135], v2 offset:0x3a00
	s_waitcnt lgkmcnt(6)
	v_mfma_f32_32x32x16_bf16 v[48:63], v[4:7], v[22:25], v[48:63]
	ds_read_b64_tr_b16 v[22:23], v2 offset:0x400
	ds_read_b64_tr_b16 v[24:25], v2 offset:0xc00
	s_waitcnt lgkmcnt(6)
	v_mfma_f32_32x32x16_bf16 v[48:63], v[8:11], v[26:29], v[48:63]
	ds_read_b64_tr_b16 v[26:27], v2 offset:0x1400
	ds_read_b64_tr_b16 v[28:29], v2 offset:0x1c00
	s_waitcnt lgkmcnt(6)
	v_mfma_f32_32x32x16_bf16 v[48:63], v[12:15], v[128:131], v[48:63]
	ds_read_b64_tr_b16 v[128:129], v2 offset:0x2400
	ds_read_b64_tr_b16 v[130:131], v2 offset:0x2c00
	s_waitcnt lgkmcnt(6)
	v_mfma_f32_32x32x16_bf16 v[48:63], v[18:21], v[132:135], v[48:63]
	ds_read_b64_tr_b16 v[132:133], v2 offset:0x3400
	ds_read_b64_tr_b16 v[134:135], v2 offset:0x3c00
	s_waitcnt lgkmcnt(6)
	v_mfma_f32_32x32x16_bf16 v[64:79], v[4:7], v[22:25], v[64:79]
	ds_read_b64_tr_b16 v[22:23], v2 offset:0x600
	ds_read_b64_tr_b16 v[24:25], v2 offset:0xe00
	s_waitcnt lgkmcnt(6)
	v_mfma_f32_32x32x16_bf16 v[64:79], v[8:11], v[26:29], v[64:79]
	ds_read_b64_tr_b16 v[26:27], v2 offset:0x1600
	ds_read_b64_tr_b16 v[28:29], v2 offset:0x1e00
	s_waitcnt lgkmcnt(6)
	v_mfma_f32_32x32x16_bf16 v[64:79], v[12:15], v[128:131], v[64:79]
	ds_read_b64_tr_b16 v[128:129], v2 offset:0x2600
	ds_read_b64_tr_b16 v[130:131], v2 offset:0x2e00
	s_waitcnt lgkmcnt(6)
	v_mfma_f32_32x32x16_bf16 v[64:79], v[18:21], v[132:135], v[64:79]
	ds_read_b64_tr_b16 v[132:133], v2 offset:0x3600
	ds_read_b64_tr_b16 v[134:135], v2 offset:0x3e00
	s_waitcnt lgkmcnt(6)
	v_mfma_f32_32x32x16_bf16 v[80:95], v[4:7], v[22:25], v[80:95]
	v_max_f32_e32 v2, v113, v112
	v_max3_f32 v2, v2, v114, v115
	v_max3_f32 v2, v2, v116, v117
	v_max3_f32 v2, v2, v118, v119
	v_max3_f32 v2, v2, v120, v121
	v_max3_f32 v2, v2, v122, v123
	v_max3_f32 v2, v2, v124, v125
	v_max3_f32 v2, v2, v126, v127
	s_waitcnt lgkmcnt(4)
	v_mfma_f32_32x32x16_bf16 v[80:95], v[8:11], v[26:29], v[80:95]
	v_max3_f32 v2, v2, v96, v97
	v_max3_f32 v2, v2, v98, v99
	v_max3_f32 v2, v2, v100, v101
	v_max3_f32 v2, v2, v102, v103
	v_max3_f32 v2, v2, v104, v105
	v_max3_f32 v2, v2, v106, v107
	v_max3_f32 v2, v2, v108, v109
	v_max3_f32 v2, v2, v110, v111
	s_waitcnt lgkmcnt(2)
	v_mfma_f32_32x32x16_bf16 v[80:95], v[12:15], v[128:131], v[80:95]
	v_mov_b32_e32 v4, v2
	s_nop 1
	v_permlane32_swap_b32_e32 v2, v4
	v_max_f32_e32 v2, v4, v2
	v_sub_f32_e32 v4, v2, v214
	v_cmp_ge_f32_e32 vcc, 0x42b504f3, v4
	v_max_f32_e32 v2, v214, v2
	s_waitcnt lgkmcnt(0)
	v_mfma_f32_32x32x16_bf16 v[80:95], v[18:21], v[132:135], v[80:95]
	s_cmp_eq_u64 vcc, exec
	s_cbranch_scc0 .Lattn0_slowA
	v_mov_b32_e32 v4, 1.0
	v_mov_b32_e32 v2, v214
.Lattn0_backA:
	s_waitcnt vmcnt(4) lgkmcnt(0)
	s_barrier
	v_add3_u32 v215, s69, v209, v208
	v_add3_u32 v216, s69, v210, v208
	v_add3_u32 v233, s69, v211, v208
	v_add3_u32 v254, s69, v212, v208
	ds_read_b128 v[234:237], v215 offset:49152
	ds_read_b128 v[238:241], v215 offset:57344
	ds_read_b128 v[242:245], v216 offset:49152
	ds_read_b128 v[246:249], v216 offset:57344
	ds_read_b128 v[250:253], v233 offset:49152
	v_mul_f32_e32 v5, 0xbe0293ee, v2
	v_fmamk_f32 v6, v112, 0x3e0293ee, v5
	v_fmamk_f32 v7, v113, 0x3e0293ee, v5
	v_fmamk_f32 v8, v114, 0x3e0293ee, v5
	v_fmamk_f32 v9, v115, 0x3e0293ee, v5
	v_fmamk_f32 v10, v116, 0x3e0293ee, v5
	v_fmamk_f32 v11, v117, 0x3e0293ee, v5
	v_fmamk_f32 v12, v118, 0x3e0293ee, v5
	v_fmamk_f32 v13, v119, 0x3e0293ee, v5
	v_fmamk_f32 v14, v120, 0x3e0293ee, v5
	v_fmamk_f32 v15, v121, 0x3e0293ee, v5
	v_fmamk_f32 v18, v122, 0x3e0293ee, v5
	v_fmamk_f32 v19, v123, 0x3e0293ee, v5
	v_fmamk_f32 v20, v124, 0x3e0293ee, v5
	v_fmamk_f32 v21, v125, 0x3e0293ee, v5
	v_fmamk_f32 v22, v126, 0x3e0293ee, v5
	v_fmamk_f32 v23, v127, 0x3e0293ee, v5
	v_fmamk_f32 v24, v96, 0x3e0293ee, v5
	v_fmamk_f32 v25, v97, 0x3e0293ee, v5
	v_fmamk_f32 v26, v98, 0x3e0293ee, v5
	v_fmamk_f32 v27, v99, 0x3e0293ee, v5
	v_fmamk_f32 v28, v100, 0x3e0293ee, v5
	v_fmamk_f32 v29, v101, 0x3e0293ee, v5
	v_fmamk_f32 v30, v102, 0x3e0293ee, v5
	v_fmamk_f32 v31, v103, 0x3e0293ee, v5
	v_fmamk_f32 v128, v104, 0x3e0293ee, v5
	v_fmamk_f32 v129, v105, 0x3e0293ee, v5
	v_fmamk_f32 v130, v106, 0x3e0293ee, v5
	v_fmamk_f32 v131, v107, 0x3e0293ee, v5
	v_fmamk_f32 v132, v108, 0x3e0293ee, v5
	v_fmamk_f32 v133, v109, 0x3e0293ee, v5
	v_fmamk_f32 v134, v110, 0x3e0293ee, v5
	v_fmac_f32_e32 v5, 0x3e0293ee, v111
	s_setprio 1
	s_waitcnt lgkmcnt(4)
	v_mfma_f32_32x32x16_bf16 v[112:127], v[234:237], v[188:191], 0
	ds_read_b128 v[234:237], v233 offset:57344
	v_exp_f32_e32 v135, v6
	v_exp_f32_e32 v136, v7
	v_exp_f32_e32 v137, v8
	v_exp_f32_e32 v138, v9
	s_waitcnt lgkmcnt(4)
	v_mfma_f32_32x32x16_bf16 v[96:111], v[238:241], v[188:191], 0
	ds_read_b128 v[238:241], v254 offset:49152
	v_exp_f32_e32 v10, v10
	v_exp_f32_e32 v11, v11
	v_exp_f32_e32 v12, v12
	s_waitcnt lgkmcnt(4)
	v_mfma_f32_32x32x16_bf16 v[112:127], v[242:245], v[184:187], v[112:127]
	ds_read_b128 v[242:245], v254 offset:57344
	s_add_i32 s4, s77, s42
	s_mov_b32 m0, s4
	s_nop 0
	global_load_lds_dwordx4 v197, s[70:71]
	v_exp_f32_e32 v13, v13
	v_exp_f32_e32 v14, v14
	v_exp_f32_e32 v15, v15
	v_exp_f32_e32 v18, v18
	s_waitcnt lgkmcnt(4)
	v_mfma_f32_32x32x16_bf16 v[96:111], v[246:249], v[184:187], v[96:111]
	ds_read_b128 v[246:249], v215 offset:49280
	v_exp_f32_e32 v19, v19
	v_exp_f32_e32 v20, v20
	v_exp_f32_e32 v21, v21
	s_waitcnt lgkmcnt(4)
	v_mfma_f32_32x32x16_bf16 v[112:127], v[250:253], v[180:183], v[112:127]
	ds_read_b128 v[250:253], v215 offset:57472
	v_exp_f32_e32 v22, v22
	v_exp_f32_e32 v23, v23
	v_exp_f32_e32 v7, v24
	v_exp_f32_e32 v24, v25
	s_waitcnt lgkmcnt(4)
	v_mfma_f32_32x32x16_bf16 v[96:111], v[234:237], v[180:183], v[96:111]
	ds_read_b128 v[234:237], v216 offset:49280
	s_addk_i32 s4, 0x400
	s_mov_b32 m0, s4
	s_nop 0
	global_load_lds_dwordx4 v198, s[70:71]
	v_exp_f32_e32 v25, v26
	v_exp_f32_e32 v26, v27
	v_exp_f32_e32 v27, v28
	s_waitcnt lgkmcnt(4)
	v_mfma_f32_32x32x16_bf16 v[112:127], v[238:241], v[176:179], v[112:127]
	ds_read_b128 v[238:241], v216 offset:57472
	v_exp_f32_e32 v28, v29
	v_exp_f32_e32 v29, v30
	v_exp_f32_e32 v30, v31
	v_exp_f32_e32 v31, v128
	s_waitcnt lgkmcnt(4)
	v_mfma_f32_32x32x16_bf16 v[96:111], v[242:245], v[176:179], v[96:111]
	ds_read_b128 v[242:245], v233 offset:49280
	v_exp_f32_e32 v128, v129
	v_exp_f32_e32 v129, v130
	v_exp_f32_e32 v130, v131
	v_exp_f32_e32 v131, v132
	s_waitcnt lgkmcnt(4)
	v_mfma_f32_32x32x16_bf16 v[112:127], v[246:249], v[172:175], v[112:127]
	ds_read_b128 v[246:249], v233 offset:57472
	s_add_u32 s4, s56, 0x4000
	s_addc_u32 s5, s57, 0
	s_add_i32 s72, s74, s97
	s_mov_b32 m0, s72
	s_nop 0
	global_load_lds_dwordx4 v199, s[4:5]
	v_exp_f32_e32 v132, v133
	v_exp_f32_e32 v133, v134
	v_exp_f32_e32 v134, v5
	s_waitcnt lgkmcnt(4)
	v_mfma_f32_32x32x16_bf16 v[96:111], v[250:253], v[172:175], v[96:111]
	ds_read_b128 v[250:253], v254 offset:49280
	v_add_f32_e32 v5, 0, v135
	v_add_f32_e32 v5, v136, v5
	v_add_f32_e32 v5, v137, v5
	v_add_f32_e32 v5, v138, v5
	v_add_f32_e32 v5, v10, v5
	v_add_f32_e32 v5, v11, v5
	v_add_f32_e32 v5, v12, v5
	v_add_f32_e32 v5, v13, v5
	s_waitcnt lgkmcnt(4)
	v_mfma_f32_32x32x16_bf16 v[112:127], v[234:237], v[168:171], v[112:127]
	ds_read_b128 v[234:237], v254 offset:57472
	v_add_f32_e32 v5, v14, v5
	v_add_f32_e32 v5, v15, v5
	v_add_f32_e32 v5, v18, v5
	v_add_f32_e32 v5, v19, v5
	v_add_f32_e32 v5, v20, v5
	v_add_f32_e32 v5, v21, v5
	v_add_f32_e32 v5, v22, v5
	s_waitcnt lgkmcnt(4)
	v_mfma_f32_32x32x16_bf16 v[96:111], v[238:241], v[168:171], v[96:111]
	s_addk_i32 s72, 0x400
	s_mov_b32 m0, s72
	s_nop 0
	global_load_lds_dwordx4 v200, s[4:5]
	v_add_f32_e32 v5, v23, v5
	v_add_f32_e32 v5, v7, v5
	v_add_f32_e32 v5, v24, v5
	v_add_f32_e32 v5, v25, v5
	v_add_f32_e32 v5, v26, v5
	v_add_f32_e32 v5, v27, v5
	v_add_f32_e32 v5, v28, v5
	s_waitcnt lgkmcnt(3)
	v_mfma_f32_32x32x16_bf16 v[112:127], v[242:245], v[164:167], v[112:127]
	v_add_f32_e32 v5, v29, v5
	v_add_f32_e32 v5, v30, v5
	v_add_f32_e32 v5, v31, v5
	v_add_f32_e32 v5, v128, v5
	v_add_f32_e32 v5, v129, v5
	v_add_f32_e32 v5, v130, v5
	v_add_f32_e32 v5, v131, v5
	s_waitcnt lgkmcnt(2)
	v_mfma_f32_32x32x16_bf16 v[96:111], v[246:249], v[164:167], v[96:111]
	v_add_f32_e32 v5, v132, v5
	v_add_f32_e32 v5, v133, v5
	v_add_f32_e32 v5, v134, v5
	v_mov_b32_e32 v6, v5
	v_cvt_pk_bf16_f32 v8, v135, v136
	v_cvt_pk_bf16_f32 v9, v137, v138
	v_cvt_pk_bf16_f32 v10, v10, v11
	s_waitcnt lgkmcnt(1)
	v_mfma_f32_32x32x16_bf16 v[112:127], v[250:253], v[160:163], v[112:127]
	s_nop 1
	v_permlane32_swap_b32_e32 v5, v6
	v_cvt_pk_bf16_f32 v11, v12, v13
	v_cvt_pk_bf16_f32 v12, v14, v15
	v_cvt_pk_bf16_f32 v13, v18, v19
	v_cvt_pk_bf16_f32 v14, v20, v21
	v_cvt_pk_bf16_f32 v15, v22, v23
	v_cvt_pk_bf16_f32 v18, v7, v24
	s_waitcnt lgkmcnt(0)
	v_mfma_f32_32x32x16_bf16 v[96:111], v[234:237], v[160:163], v[96:111]
	v_cvt_pk_bf16_f32 v19, v25, v26
	v_cvt_pk_bf16_f32 v20, v27, v28
	v_cvt_pk_bf16_f32 v21, v29, v30
	v_cvt_pk_bf16_f32 v22, v31, v128
	v_cvt_pk_bf16_f32 v23, v129, v130
	v_cvt_pk_bf16_f32 v24, v131, v132
	v_cvt_pk_bf16_f32 v25, v133, v134
	s_setprio 0
	v_add_u32_e32 v7, s77, v206
	ds_read_b64_tr_b16 v[26:27], v7 offset:0
	ds_read_b64_tr_b16 v[28:29], v7 offset:0x800
	ds_read_b64_tr_b16 v[128:129], v7 offset:0x1000
	ds_read_b64_tr_b16 v[130:131], v7 offset:0x1800
	ds_read_b64_tr_b16 v[132:133], v7 offset:0x2000
	ds_read_b64_tr_b16 v[134:135], v7 offset:0x2800
	ds_read_b64_tr_b16 v[136:137], v7 offset:0x3000
	ds_read_b64_tr_b16 v[138:139], v7 offset:0x3800
	s_waitcnt lgkmcnt(6)
	s_nop 0
	v_mfma_f32_32x32x16_bf16 v[32:47], v[8:11], v[26:29], v[32:47]
	ds_read_b64_tr_b16 v[26:27], v7 offset:0x200
	ds_read_b64_tr_b16 v[28:29], v7 offset:0xa00
	s_waitcnt lgkmcnt(6)
	v_mfma_f32_32x32x16_bf16 v[32:47], v[12:15], v[128:131], v[32:47]
	ds_read_b64_tr_b16 v[128:129], v7 offset:0x1200
	ds_read_b64_tr_b16 v[130:131], v7 offset:0x1a00
	s_waitcnt lgkmcnt(6)
	v_mfma_f32_32x32x16_bf16 v[32:47], v[18:21], v[132:135], v[32:47]
	ds_read_b64_tr_b16 v[132:133], v7 offset:0x2200
	ds_read_b64_tr_b16 v[134:135], v7 offset:0x2a00
	s_waitcnt lgkmcnt(6)
	v_mfma_f32_32x32x16_bf16 v[32:47], v[22:25], v[136:139], v[32:47]
	ds_read_b64_tr_b16 v[136:137], v7 offset:0x3200
	ds_read_b64_tr_b16 v[138:139], v7 offset:0x3a00
	s_waitcnt lgkmcnt(6)
	v_mfma_f32_32x32x16_bf16 v[48:63], v[8:11], v[26:29], v[48:63]
	ds_read_b64_tr_b16 v[26:27], v7 offset:0x400
	ds_read_b64_tr_b16 v[28:29], v7 offset:0xc00
	s_waitcnt lgkmcnt(6)
	v_mfma_f32_32x32x16_bf16 v[48:63], v[12:15], v[128:131], v[48:63]
	ds_read_b64_tr_b16 v[128:129], v7 offset:0x1400
	ds_read_b64_tr_b16 v[130:131], v7 offset:0x1c00
	s_waitcnt lgkmcnt(6)
	v_mfma_f32_32x32x16_bf16 v[48:63], v[18:21], v[132:135], v[48:63]
	ds_read_b64_tr_b16 v[132:133], v7 offset:0x2400
	ds_read_b64_tr_b16 v[134:135], v7 offset:0x2c00
	s_waitcnt lgkmcnt(6)
	v_mfma_f32_32x32x16_bf16 v[48:63], v[22:25], v[136:139], v[48:63]
	ds_read_b64_tr_b16 v[136:137], v7 offset:0x3400
	ds_read_b64_tr_b16 v[138:139], v7 offset:0x3c00
	s_waitcnt lgkmcnt(6)
	v_mfma_f32_32x32x16_bf16 v[64:79], v[8:11], v[26:29], v[64:79]
	ds_read_b64_tr_b16 v[26:27], v7 offset:0x600
	ds_read_b64_tr_b16 v[28:29], v7 offset:0xe00
	s_waitcnt lgkmcnt(6)
	v_mfma_f32_32x32x16_bf16 v[64:79], v[12:15], v[128:131], v[64:79]
	ds_read_b64_tr_b16 v[128:129], v7 offset:0x1600
	ds_read_b64_tr_b16 v[130:131], v7 offset:0x1e00
	s_waitcnt lgkmcnt(6)
	v_mfma_f32_32x32x16_bf16 v[64:79], v[18:21], v[132:135], v[64:79]
	ds_read_b64_tr_b16 v[132:133], v7 offset:0x2600
	ds_read_b64_tr_b16 v[134:135], v7 offset:0x2e00
	s_waitcnt lgkmcnt(6)
	v_mfma_f32_32x32x16_bf16 v[64:79], v[22:25], v[136:139], v[64:79]
	ds_read_b64_tr_b16 v[136:137], v7 offset:0x3600
	ds_read_b64_tr_b16 v[138:139], v7 offset:0x3e00
	s_waitcnt lgkmcnt(6)
	v_mfma_f32_32x32x16_bf16 v[80:95], v[8:11], v[26:29], v[80:95]
	v_max_f32_e32 v7, v113, v112
	v_max3_f32 v7, v7, v114, v115
	v_max3_f32 v7, v7, v116, v117
	v_max3_f32 v7, v7, v118, v119
	v_max3_f32 v7, v7, v120, v121
	v_max3_f32 v7, v7, v122, v123
	v_max3_f32 v7, v7, v124, v125
	v_max3_f32 v7, v7, v126, v127
	s_waitcnt lgkmcnt(4)
	v_mfma_f32_32x32x16_bf16 v[80:95], v[12:15], v[128:131], v[80:95]
	v_max3_f32 v7, v7, v96, v97
	v_max3_f32 v7, v7, v98, v99
	v_max3_f32 v7, v7, v100, v101
	v_max3_f32 v7, v7, v102, v103
	v_max3_f32 v7, v7, v104, v105
	v_max3_f32 v7, v7, v106, v107
	v_max3_f32 v7, v7, v108, v109
	v_max3_f32 v7, v7, v110, v111
	s_waitcnt lgkmcnt(2)
	v_mfma_f32_32x32x16_bf16 v[80:95], v[18:21], v[132:135], v[80:95]
	v_mov_b32_e32 v8, v7
	s_nop 1
	v_permlane32_swap_b32_e32 v7, v8
	v_max_f32_e32 v7, v8, v7
	v_sub_f32_e32 v8, v7, v2
	v_cmp_ge_f32_e32 vcc, 0x42b504f3, v8
	v_max_f32_e32 v8, v2, v7
	s_waitcnt lgkmcnt(0)
	v_mfma_f32_32x32x16_bf16 v[80:95], v[22:25], v[136:139], v[80:95]
	s_cmp_eq_u64 vcc, exec
	s_cbranch_scc0 .Lattn0_slowB
	v_mov_b32_e32 v7, 1.0
	v_mov_b32_e32 v214, v2
